# gated small_gemm partial-sum reduction: 16 serialized LDS reads batched (on top of ssm_a/ssm_b/conversion-tail changes)
# baseline (speedup 1.0000x reference)
.LBB0_103:
	s_ashr_i32 s0, s23, 31
	s_lshr_b32 s0, s0, 27
	s_add_i32 s0, s23, s0
	s_and_b32 s24, s0, 0xffffffe0
	s_ashr_i32 s1, s0, 5
	s_addk_i32 s24, 0x4000
	s_lshl_b32 s25, s1, 10
	s_lshl_b32 s1, s1, 11
	v_or_b32_e32 v6, s24, v176
	s_sub_i32 s0, s8, s25
	s_sub_i32 s1, s19, s1
	v_ashrrev_i32_e32 v7, 31, v6
	s_and_b32 s1, s1, 0xffffff00
	s_and_b32 s0, s0, 0x60
	v_lshlrev_b64 v[6:7], 11, v[6:7]
	s_or_b32 s0, s1, s0
	v_lshl_add_u64 v[62:63], v[2:3], 0, v[6:7]
	v_or_b32_e32 v22, s0, v176
	v_add_co_u32_e64 v72, s[0:1], s93, v62
	global_load_dwordx4 v[6:9], v[62:63], off
	global_load_dwordx4 v[46:49], v[62:63], off offset:64
	v_addc_co_u32_e64 v73, s[0:1], 0, v63, s[0:1]
	v_or_b32_e32 v18, 16, v22
	v_or_b32_e32 v24, 0x80, v22
	v_or_b32_e32 v30, 0x90, v22
	global_load_dwordx4 v[42:45], v[72:73], off
	v_ashrrev_i32_e32 v23, 31, v22
	v_ashrrev_i32_e32 v19, 31, v18
	v_ashrrev_i32_e32 v25, 31, v24
	v_ashrrev_i32_e32 v31, 31, v30
	v_lshlrev_b64 v[10:11], 11, v[22:23]
	v_lshlrev_b64 v[18:19], 11, v[18:19]
	v_lshlrev_b64 v[22:23], 11, v[24:25]
	v_lshlrev_b64 v[30:31], 11, v[30:31]
	v_lshl_add_u64 v[64:65], v[4:5], 0, v[10:11]
	v_lshl_add_u64 v[66:67], v[4:5], 0, v[18:19]
	v_lshl_add_u64 v[68:69], v[4:5], 0, v[22:23]
	v_lshl_add_u64 v[70:71], v[4:5], 0, v[30:31]
	global_load_dwordx4 v[10:13], v[64:65], off
	global_load_dwordx4 v[18:21], v[66:67], off
	global_load_dwordx4 v[22:25], v[68:69], off
	global_load_dwordx4 v[54:57], v[68:69], off offset:64
	global_load_dwordx4 v[34:37], v[70:71], off
	global_load_dwordx4 v[58:61], v[70:71], off offset:64
	v_add_u32_e32 v17, 0x1000, v16
	s_waitcnt vmcnt(0)
	v_mfma_f32_16x16x32_bf16 v[26:29], v[6:9], v[10:13], 0
	global_load_dwordx4 v[50:53], v[66:67], off offset:64
	v_mfma_f32_16x16x32_bf16 v[30:33], v[6:9], v[18:21], 0
	v_mfma_f32_16x16x32_bf16 v[38:41], v[6:9], v[22:25], 0
	v_mfma_f32_16x16x32_bf16 v[6:9], v[6:9], v[34:37], 0
	v_mfma_f32_16x16x32_bf16 v[10:13], v[42:45], v[10:13], 0
	v_mfma_f32_16x16x32_bf16 v[18:21], v[42:45], v[18:21], 0
	v_mfma_f32_16x16x32_bf16 v[22:25], v[42:45], v[22:25], 0
	v_mfma_f32_16x16x32_bf16 v[34:37], v[42:45], v[34:37], 0
	global_load_dwordx4 v[42:45], v[64:65], off offset:64
	v_mfma_f32_16x16x32_bf16 v[38:41], v[46:49], v[54:57], v[38:41]
	v_mfma_f32_16x16x32_bf16 v[6:9], v[46:49], v[58:61], v[6:9]
	s_waitcnt vmcnt(0)
	v_mfma_f32_16x16x32_bf16 v[26:29], v[46:49], v[42:45], v[26:29]
	v_mfma_f32_16x16x32_bf16 v[30:33], v[46:49], v[50:53], v[30:33]
	global_load_dwordx4 v[46:49], v[72:73], off offset:64
	s_waitcnt vmcnt(0)
	v_mfma_f32_16x16x32_bf16 v[10:13], v[46:49], v[42:45], v[10:13]
	global_load_dwordx4 v[42:45], v[62:63], off offset:128
	v_mfma_f32_16x16x32_bf16 v[18:21], v[46:49], v[50:53], v[18:21]
	global_load_dwordx4 v[50:53], v[66:67], off offset:128
	v_mfma_f32_16x16x32_bf16 v[22:25], v[46:49], v[54:57], v[22:25]
	global_load_dwordx4 v[54:57], v[68:69], off offset:128
	v_mfma_f32_16x16x32_bf16 v[34:37], v[46:49], v[58:61], v[34:37]
	global_load_dwordx4 v[46:49], v[64:65], off offset:128
	global_load_dwordx4 v[58:61], v[70:71], off offset:128
	s_waitcnt vmcnt(0)
	v_mfma_f32_16x16x32_bf16 v[26:29], v[42:45], v[46:49], v[26:29]
	v_mfma_f32_16x16x32_bf16 v[30:33], v[42:45], v[50:53], v[30:33]
	v_mfma_f32_16x16x32_bf16 v[38:41], v[42:45], v[54:57], v[38:41]
	v_mfma_f32_16x16x32_bf16 v[6:9], v[42:45], v[58:61], v[6:9]
	global_load_dwordx4 v[42:45], v[72:73], off offset:128
	s_waitcnt vmcnt(0)
	v_mfma_f32_16x16x32_bf16 v[10:13], v[42:45], v[46:49], v[10:13]
	global_load_dwordx4 v[46:49], v[62:63], off offset:192
	v_mfma_f32_16x16x32_bf16 v[18:21], v[42:45], v[50:53], v[18:21]
	global_load_dwordx4 v[50:53], v[64:65], off offset:192
	v_mfma_f32_16x16x32_bf16 v[22:25], v[42:45], v[54:57], v[22:25]
	v_mfma_f32_16x16x32_bf16 v[34:37], v[42:45], v[58:61], v[34:37]
	global_load_dwordx4 v[42:45], v[66:67], off offset:192
	global_load_dwordx4 v[54:57], v[68:69], off offset:192
	global_load_dwordx4 v[58:61], v[70:71], off offset:192
	global_load_dwordx4 v[62:65], v[72:73], off offset:192
	s_waitcnt vmcnt(0)
	v_mfma_f32_16x16x32_bf16 v[26:29], v[46:49], v[50:53], v[26:29]
	s_waitcnt lgkmcnt(0)
	s_barrier
	v_mfma_f32_16x16x32_bf16 v[30:33], v[46:49], v[42:45], v[30:33]
	s_nop 7
	ds_write2_b32 v16, v26, v30 offset1:16
	ds_write2_b32 v16, v27, v31 offset0:68 offset1:84
	v_mfma_f32_16x16x32_bf16 v[38:41], v[46:49], v[54:57], v[38:41]
	v_mfma_f32_16x16x32_bf16 v[6:9], v[46:49], v[58:61], v[6:9]
	ds_write2_b32 v16, v28, v32 offset0:136 offset1:152
	ds_write2_b32 v16, v29, v33 offset0:204 offset1:220
	s_nop 5
	ds_write2_b32 v16, v38, v6 offset0:32 offset1:48
	ds_write2_b32 v16, v39, v7 offset0:100 offset1:116
	ds_write2_b32 v16, v40, v8 offset0:168 offset1:184
	ds_write2_b32 v16, v41, v9 offset0:236 offset1:252
	v_mfma_f32_16x16x32_bf16 v[10:13], v[62:65], v[50:53], v[10:13]
	v_mfma_f32_16x16x32_bf16 v[6:9], v[62:65], v[42:45], v[18:21]
	s_nop 7
	ds_write2_b32 v17, v10, v6 offset0:64 offset1:80
	ds_write2_b32 v17, v11, v7 offset0:132 offset1:148
	v_add_u32_e32 v10, 0x1400, v16
	v_mfma_f32_16x16x32_bf16 v[18:21], v[62:65], v[54:57], v[22:25]
	ds_write2_b32 v17, v12, v8 offset0:200 offset1:216
	ds_write2_b32 v10, v13, v9 offset0:12 offset1:28
	v_mfma_f32_16x16x32_bf16 v[6:9], v[62:65], v[58:61], v[34:37]
	s_nop 7
	ds_write2_b32 v17, v18, v6 offset0:96 offset1:112
	ds_write2_b32 v17, v19, v7 offset0:164 offset1:180
	ds_write2_b32 v17, v20, v8 offset0:232 offset1:248
	ds_write2_b32 v10, v21, v9 offset0:44 offset1:60
	s_waitcnt lgkmcnt(0)
	s_barrier
	s_and_saveexec_b64 s[0:1], vcc
	s_cbranch_execz .LBB0_102
	ds_read_b128 v[206:209], v15
	ds_read_b128 v[214:217], v15 offset:8704
	ds_read_b128 v[218:221], v15 offset:17408
	ds_read_b128 v[222:225], v15 offset:26112
	ds_read_b128 v[226:229], v15 offset:34816
	ds_read_b128 v[230:233], v15 offset:43520
	ds_read_b128 v[234:237], v15 offset:52224
	ds_read_b128 v[238:241], v15 offset:60928
	ds_read_b128 v[210:213], v15 offset:128
	ds_read_b128 v[242:245], v15 offset:8832
	ds_read_b128 v[246:249], v15 offset:17536
	ds_read_b128 v[162:165], v15 offset:26240
	ds_read_b128 v[166:169], v15 offset:34944
	ds_read_b128 v[170:173], v15 offset:43648
	ds_read_b128 v[178:181], v15 offset:52352
	s_waitcnt lgkmcnt(7)
	ds_read_b128 v[182:185], v15 offset:61056
	s_sub_i32 s25, 0, s25
	s_add_i32 s25, s25, s8
	v_pk_add_f32 v[10:11], v[208:209], 0 op_sel_hi:[1,0]
	v_pk_add_f32 v[12:13], v[206:207], 0 op_sel_hi:[1,0]
	v_pk_add_f32 v[10:11], v[10:11], v[216:217]
	v_pk_add_f32 v[12:13], v[12:13], v[214:215]
	v_pk_add_f32 v[10:11], v[10:11], v[220:221]
	v_pk_add_f32 v[12:13], v[12:13], v[218:219]
	v_pk_add_f32 v[10:11], v[10:11], v[224:225]
	v_pk_add_f32 v[12:13], v[12:13], v[222:223]
	v_pk_add_f32 v[10:11], v[10:11], v[228:229]
	v_pk_add_f32 v[12:13], v[12:13], v[226:227]
	v_pk_add_f32 v[10:11], v[10:11], v[232:233]
	v_pk_add_f32 v[12:13], v[12:13], v[230:231]
	v_pk_add_f32 v[10:11], v[10:11], v[236:237]
	v_pk_add_f32 v[12:13], v[12:13], v[234:235]
	v_pk_add_f32 v[8:9], v[10:11], v[240:241]
	v_pk_add_f32 v[10:11], v[12:13], v[238:239]
	s_waitcnt lgkmcnt(0)
	v_pk_add_f32 v[6:7], v[212:213], 0 op_sel_hi:[1,0]
	v_pk_add_f32 v[12:13], v[210:211], 0 op_sel_hi:[1,0]
	v_pk_add_f32 v[6:7], v[6:7], v[244:245]
	v_pk_add_f32 v[12:13], v[12:13], v[242:243]
	v_pk_add_f32 v[6:7], v[6:7], v[248:249]
	v_pk_add_f32 v[12:13], v[12:13], v[246:247]
	v_pk_add_f32 v[6:7], v[6:7], v[164:165]
	v_pk_add_f32 v[12:13], v[12:13], v[162:163]
	v_pk_add_f32 v[6:7], v[6:7], v[168:169]
	v_pk_add_f32 v[12:13], v[12:13], v[166:167]
	v_pk_add_f32 v[6:7], v[6:7], v[172:173]
	v_pk_add_f32 v[12:13], v[12:13], v[170:171]
	v_pk_add_f32 v[6:7], v[6:7], v[180:181]
	v_pk_add_f32 v[22:23], v[12:13], v[178:179]
	v_pk_add_f32 v[12:13], v[6:7], v[184:185]
	v_add_u32_e32 v6, s25, v14
	v_ashrrev_i32_e32 v7, 31, v6
	v_pk_add_f32 v[26:27], v[22:23], v[182:183]
	v_lshlrev_b64 v[22:23], 2, v[6:7]
	v_lshl_add_u64 v[18:19], s[40:41], 0, v[22:23]
	v_lshl_add_u64 v[22:23], s[2:3], 0, v[22:23]
	global_load_dwordx4 v[18:21], v[18:19], off
	s_nop 0
	global_load_dwordx4 v[22:25], v[22:23], off
	s_waitcnt vmcnt(1)
	v_add_f32_e32 v10, v10, v18
	v_add_f32_e32 v8, v8, v20
	s_waitcnt vmcnt(0)
	v_add_f32_e32 v17, v26, v22
	v_add_f32_e32 v12, v12, v24
	v_mul_f32_e32 v17, 0xbfb8aa3b, v17
	v_mul_f32_e32 v12, 0xbfb8aa3b, v12
	v_exp_f32_e32 v17, v17
	v_exp_f32_e32 v12, v12
	v_add_f32_e32 v11, v11, v19
	v_add_f32_e32 v17, 1.0, v17
	v_add_f32_e32 v12, 1.0, v12
	v_rcp_f32_e32 v17, v17
	v_rcp_f32_e32 v12, v12
	v_mul_f32_e32 v10, v10, v17
	v_add_f32_e32 v17, v27, v23
	v_mul_f32_e32 v12, v8, v12
	v_add_f32_e32 v8, v9, v21
	v_add_f32_e32 v9, v13, v25
	v_mul_f32_e32 v17, 0xbfb8aa3b, v17
	v_mul_f32_e32 v9, 0xbfb8aa3b, v9
	v_exp_f32_e32 v17, v17
	v_exp_f32_e32 v9, v9
	v_add_f32_e32 v17, 1.0, v17
	v_add_f32_e32 v9, 1.0, v9
	v_rcp_f32_e32 v17, v17
	v_rcp_f32_e32 v9, v9
	v_mul_f32_e32 v11, v11, v17
	v_mul_f32_e32 v9, v8, v9
	v_cvt_pk_bf16_f32 v8, v10, v11
	v_add_u32_e32 v10, s24, v0
	v_ashrrev_i32_e32 v11, 31, v10
	v_lshlrev_b64 v[10:11], 11, v[10:11]
	v_lshl_add_u64 v[10:11], s[20:21], 0, v[10:11]
	v_lshl_add_u64 v[6:7], v[6:7], 1, v[10:11]
	v_cvt_pk_bf16_f32 v9, v12, v9
	global_store_dwordx2 v[6:7], v[8:9], off
	s_branch .LBB0_102
